# stagger only the (out-proj, norm2) pairs for the odd teams; (down, next norm) runs whole-phase for every team
# baseline (speedup 1.0000x reference)
.LBB0_15:
	v_readlane_b32 s2, v255, 48
	s_cmp_eq_u32 s2, 0
	s_cbranch_scc1 .Lsq_std
	s_mov_b32 s3, 0x8040
	s_bitcmp1_b32 s3, s80
	s_cbranch_scc0 .Lsq_inN
	s_add_i32 s80, s80, 1
	s_mov_b64 s[0:1], -1
	s_branch .LBB0_423

.Lsq_std:
	s_add_i32 s80, s80, 1
	s_cmp_ge_i32 s80, s81
	s_mov_b64 s[0:1], -1
	s_cbranch_scc1 .LBB0_10
	s_mov_b32 s2, 0
	s_bitcmp1_b32 s61, 6
	s_cbranch_scc0 .Lsq_setm
	s_mov_b32 s3, 0x8040
	s_bitcmp1_b32 s3, s80
	s_cselect_b32 s2, 1, 0

.Ltb_done:
	s_cmp_lg_u32 s80, 11
	s_cbranch_scc1 .Ltb_nodep
	v_readlane_b32 s6, v254, 44
	v_readlane_b32 s7, v254, 45
	s_bfe_u32 s13, s61, 0x60003
	s_and_b32 s14, s13, 7
	s_lshr_b32 s13, s13, 3
	s_lshl_b32 s15, s14, 4
	s_add_i32 s15, s15, s13
	s_add_i32 s2, s15, 8
	s_mul_i32 s16, s15, 31
	s_mul_i32 s17, s16, 0xba3
	s_lshr_b32 s17, s17, 16
	s_add_i32 s16, s16, 30
	s_mul_i32 s16, s16, 0xba3
	s_lshr_b32 s16, s16, 16
	s_min_u32 s16, s16, 0x7f
	s_add_i32 s20, s17, 0
	s_cmp_le_u32 s20, s16
	s_cselect_b32 s20, s20, s15
	s_and_b32 s24, s20, 1
	s_lshl_b32 s24, s24, 2
	s_add_i32 s24, s24, 20
	s_lshr_b32 s3, s20, 4
	s_lshl_b32 s3, s3, 6
	s_and_b32 s20, s20, 7
	s_lshl_b32 s20, s20, 2
	s_add_i32 s20, s20, s3
	s_add_i32 s20, s20, 0x300
	v_mov_b32_e32 v5, s20
	s_add_i32 s20, s17, 1
	s_cmp_le_u32 s20, s16
	s_cselect_b32 s20, s20, s15
	s_and_b32 s25, s20, 1
	s_lshl_b32 s25, s25, 2
	s_add_i32 s25, s25, 20
	s_lshr_b32 s3, s20, 4
	s_lshl_b32 s3, s3, 6
	s_and_b32 s20, s20, 7
	s_lshl_b32 s20, s20, 2
	s_add_i32 s20, s20, s3
	s_add_i32 s20, s20, 0x300
	v_mov_b32_e32 v6, s20
	s_add_i32 s20, s17, 2
	s_cmp_le_u32 s20, s16
	s_cselect_b32 s20, s20, s15
	s_and_b32 s12, s20, 1
	s_lshl_b32 s12, s12, 2
	s_add_i32 s12, s12, 20
	s_lshr_b32 s3, s20, 4
	s_lshl_b32 s3, s3, 6
	s_and_b32 s20, s20, 7
	s_lshl_b32 s20, s20, 2
	s_add_i32 s20, s20, s3
	s_add_i32 s20, s20, 0x300
	v_mov_b32_e32 v7, s20
	s_mul_i32 s16, s2, 31
	s_mul_i32 s17, s16, 0xba3
	s_lshr_b32 s17, s17, 16
	s_add_i32 s16, s16, 30
	s_mul_i32 s16, s16, 0xba3
	s_lshr_b32 s16, s16, 16
	s_min_u32 s16, s16, 0x7f
	s_add_i32 s20, s17, 0
	s_cmp_le_u32 s20, s16
	s_cselect_b32 s20, s20, s15
	s_and_b32 s13, s20, 1
	s_lshl_b32 s13, s13, 2
	s_add_i32 s13, s13, 20
	s_lshr_b32 s3, s20, 4
	s_lshl_b32 s3, s3, 6
	s_and_b32 s20, s20, 7
	s_lshl_b32 s20, s20, 2
	s_add_i32 s20, s20, s3
	s_add_i32 s20, s20, 0x300
	v_mov_b32_e32 v8, s20
	s_add_i32 s20, s17, 1
	s_cmp_le_u32 s20, s16
	s_cselect_b32 s20, s20, s15
	s_and_b32 s14, s20, 1
	s_lshl_b32 s14, s14, 2
	s_add_i32 s14, s14, 20
	s_lshr_b32 s3, s20, 4
	s_lshl_b32 s3, s3, 6
	s_and_b32 s20, s20, 7
	s_lshl_b32 s20, s20, 2
	s_add_i32 s20, s20, s3
	s_add_i32 s20, s20, 0x300
	v_mov_b32_e32 v9, s20
	s_add_i32 s20, s17, 2
	s_cmp_le_u32 s20, s16
	s_cselect_b32 s20, s20, s15
	s_and_b32 s19, s20, 1
	s_lshl_b32 s19, s19, 2
	s_add_i32 s19, s19, 20
	s_lshr_b32 s3, s20, 4
	s_lshl_b32 s3, s3, 6
	s_and_b32 s20, s20, 7
	s_lshl_b32 s20, s20, 2
	s_add_i32 s20, s20, s3
	s_add_i32 s20, s20, 0x300
	v_mov_b32_e32 v10, s20
	s_mov_b32 s21, 0
